# v28 + combine_c: 16-lane sum-of-squares reduction via 4 DPP adds instead of 4 serial ds_bpermute round trips
# baseline (speedup 1.0000x reference)
; DI void unpack8(const u32x4 w, float* x) { x[0] = bflo(w.x); x[1] = bfhi(w.x); x[2] = bflo(w.y); x[3] = bfhi(w.y); x[4] = bflo(w.z); x[5] = bfhi(w.z); x[6] = bflo(w.w); x[7] = bfhi(w.w); }
; DI u32x4 pack8(const float* x) { u32x4 w; w.x = pk2(x[0], x[1]); w.y = pk2(x[2], x[3]); w.z = pk2(x[4], x[5]); w.w = pk2(x[6], x[7]); return w; }
; DI void combine_c(const bf16_t* OC, bf16_t* AO, const float* sub_gain, float lam, float oml, int gtid, int gthreads) {
;     for (int idx = gtid; idx < TC * 128; idx += gthreads) {
;         const int j = idx & 15, h = (idx >> 4) & 7, row = idx >> 7;
;         const __attribute__((address_space(1))) bf16_t* p = (const __attribute__((address_space(1))) bf16_t*)OC + (size_t)row * 2048 + h * 256 + j * 8;
;         float a[8], b[8], y[8]; unpack8(*(const __attribute__((address_space(1))) u32x4*)p, a); unpack8(*(const __attribute__((address_space(1))) u32x4*)(p + 128), b);
;         float ss = 0.f;
; #pragma unroll
;         for (int e = 0; e < 8; ++e) { a[e] = a[e] - lam * b[e]; ss += a[e] * a[e]; }
;         ss += __shfl_xor(ss, 1); ss += __shfl_xor(ss, 2); ss += __shfl_xor(ss, 4); ss += __shfl_xor(ss, 8);
;         const float rstd = 1.0f / sqrtf(ss * (1.f / 128.f) + NORM_EPS) * oml;
; #pragma unroll
;         for (int e = 0; e < 8; ++e) y[e] = a[e] * rstd * sub_gain[8 * j + e];
;         *(__attribute__((address_space(1))) u32x4*)((__attribute__((address_space(1))) bf16_t*)AO + (size_t)row * 1024 + h * 128 + j * 8) = pack8(y);
;     }
.LBB0_325:
	v_ashrrev_i32_e32 v24, 7, v202
	v_ashrrev_i32_e32 v25, 31, v24
	v_bfe_u32 v7, v202, 4, 3
	v_lshlrev_b64 v[10:11], 12, v[24:25]
	v_mov_b32_e32 v9, v195
	v_and_b32_e32 v16, 0x78, v6
	v_lshlrev_b32_e32 v8, 9, v7
	v_lshl_add_u64 v[10:11], s[30:31], 0, v[10:11]
	v_mov_b32_e32 v27, v195
	v_lshlrev_b32_e32 v26, 1, v16
	v_lshl_add_u64 v[8:9], v[10:11], 0, v[8:9]
	v_lshl_add_u64 v[12:13], v[8:9], 0, v[26:27]
	global_load_dwordx4 v[8:11], v[12:13], off
	s_nop 0
	global_load_dwordx4 v[12:15], v[12:13], off offset:256
	v_lshlrev_b32_e32 v194, 8, v7
	v_lshlrev_b32_e32 v7, 2, v16
	global_load_dwordx4 v[16:19], v7, s[12:13] offset:16
	global_load_dwordx4 v[20:23], v7, s[12:13]
	v_lshlrev_b64 v[24:25], 11, v[24:25]
	v_lshl_add_u64 v[24:25], s[72:73], 0, v[24:25]
	v_lshl_add_u64 v[24:25], v[24:25], 0, v[194:195]
	v_lshl_add_u64 v[24:25], v[24:25], 0, v[26:27]
	v_add_u32_e32 v202, s64, v202
	s_mov_b32 s0, 0x1fffff
	v_cmp_lt_i32_e32 vcc, s0, v202
	s_or_b64 s[36:37], vcc, s[36:37]
	v_add_u32_e32 v6, s66, v6
	s_waitcnt vmcnt(3)
	v_lshlrev_b32_e32 v26, 16, v11
	v_and_b32_e32 v27, 0xffff0000, v11
	s_waitcnt vmcnt(2)
	v_lshlrev_b32_e32 v28, 16, v15
	v_and_b32_e32 v29, 0xffff0000, v15
	v_lshlrev_b32_e32 v30, 16, v10
	v_and_b32_e32 v31, 0xffff0000, v10
	v_lshlrev_b32_e32 v10, 16, v14
	v_and_b32_e32 v11, 0xffff0000, v14
	v_lshlrev_b32_e32 v14, 16, v9
	v_and_b32_e32 v15, 0xffff0000, v9
	v_lshlrev_b32_e32 v34, 16, v8
	v_and_b32_e32 v35, 0xffff0000, v8
	v_lshlrev_b32_e32 v8, 16, v12
	v_and_b32_e32 v9, 0xffff0000, v12
	v_lshlrev_b32_e32 v32, 16, v13
	v_and_b32_e32 v33, 0xffff0000, v13
	v_pk_fma_f32 v[8:9], v[0:1], v[8:9], v[34:35] neg_lo:[1,0,0] neg_hi:[1,0,0]
	v_pk_fma_f32 v[14:15], v[0:1], v[32:33], v[14:15] neg_lo:[1,0,0] neg_hi:[1,0,0]
	v_pk_mul_f32 v[32:33], v[8:9], v[8:9]
	v_pk_fma_f32 v[10:11], v[0:1], v[10:11], v[30:31] neg_lo:[1,0,0] neg_hi:[1,0,0]
	v_pk_mul_f32 v[30:31], v[14:15], v[14:15]
	v_add_f32_e32 v7, v32, v33
	v_add_f32_e32 v7, v30, v7
	v_pk_fma_f32 v[12:13], v[0:1], v[28:29], v[26:27] neg_lo:[1,0,0] neg_hi:[1,0,0]
	v_pk_mul_f32 v[28:29], v[10:11], v[10:11]
	v_add_f32_e32 v7, v31, v7
	v_add_f32_e32 v7, v28, v7
	v_pk_mul_f32 v[26:27], v[12:13], v[12:13]
	v_add_f32_e32 v7, v29, v7
	v_add_f32_e32 v7, v26, v7
	v_add_f32_e32 v7, v27, v7
	s_nop 1
	v_add_f32_dpp v7, v7, v7 quad_perm:[1,0,3,2] row_mask:0xf bank_mask:0xf
	s_nop 1
	v_add_f32_dpp v7, v7, v7 quad_perm:[2,3,0,1] row_mask:0xf bank_mask:0xf
	s_nop 1
	v_add_f32_dpp v7, v7, v7 row_half_mirror row_mask:0xf bank_mask:0xf
	s_nop 1
	v_add_f32_dpp v7, v7, v7 row_mirror row_mask:0xf bank_mask:0xf
	v_fmamk_f32 v7, v7, 0x3c000000, v237
	v_mul_f32_e32 v26, 0x4f800000, v7
	v_cmp_gt_f32_e32 vcc, s68, v7
	s_nop 1
	v_cndmask_b32_e32 v7, v7, v26, vcc
	v_sqrt_f32_e32 v26, v7
	s_nop 0
	v_add_u32_e32 v27, -1, v26
	v_add_u32_e32 v28, 1, v26
	v_fma_f32 v29, -v27, v26, v7
	v_fma_f32 v30, -v28, v26, v7
	v_cmp_ge_f32_e64 s[0:1], 0, v29
	s_nop 1
	v_cndmask_b32_e64 v26, v26, v27, s[0:1]
	v_cmp_lt_f32_e64 s[0:1], 0, v30
	s_nop 1
	v_cndmask_b32_e64 v26, v26, v28, s[0:1]
	v_mul_f32_e32 v27, 0x37800000, v26
	v_cndmask_b32_e32 v26, v26, v27, vcc
	v_cmp_class_f32_e32 vcc, v7, v238
	s_nop 1
	v_cndmask_b32_e32 v7, v26, v7, vcc
	v_div_scale_f32 v26, s[0:1], v7, v7, 1.0
	v_rcp_f32_e32 v28, v26
	v_div_scale_f32 v27, vcc, 1.0, v7, 1.0
	v_fma_f32 v29, -v26, v28, 1.0
	v_fmac_f32_e32 v28, v29, v28
	v_mul_f32_e32 v29, v27, v28
	v_fma_f32 v30, -v26, v29, v27
	v_fmac_f32_e32 v29, v30, v28
	v_fma_f32 v26, -v26, v29, v27
	v_div_fmas_f32 v26, v26, v28, v29
	v_div_fixup_f32 v7, v26, v7, 1.0
	v_mul_f32_e32 v26, s67, v7
	v_pk_mul_f32 v[8:9], v[8:9], v[26:27] op_sel_hi:[1,0]
	v_pk_mul_f32 v[14:15], v[14:15], v[26:27] op_sel_hi:[1,0]
	v_pk_mul_f32 v[10:11], v[10:11], v[26:27] op_sel_hi:[1,0]
	v_pk_mul_f32 v[12:13], v[12:13], v[26:27] op_sel_hi:[1,0]
	s_waitcnt vmcnt(0)
	v_pk_mul_f32 v[8:9], v[20:21], v[8:9]
	v_pk_mul_f32 v[14:15], v[22:23], v[14:15]
	v_pk_mul_f32 v[10:11], v[16:17], v[10:11]
	v_pk_mul_f32 v[12:13], v[18:19], v[12:13]
	v_cvt_pk_bf16_f32 v8, v8, v9
	v_cvt_pk_bf16_f32 v9, v14, v15
	v_cvt_pk_bf16_f32 v10, v10, v11
	v_cvt_pk_bf16_f32 v11, v12, v13
	global_store_dwordx4 v[24:25], v[8:11], off
	s_andn2_b64 exec, exec, s[36:37]
	s_cbranch_execnz .LBB0_325
